# SEAM(0): replaced single-counter cooperative grid sync by the two-level XCD barrier used at the other seams
# speedup vs baseline: 1.0145x; 1.0047x over previous
; #define LAS __attribute__((address_space(3)))
; __device__ __forceinline__ int get_tid() { int t = __builtin_amdgcn_workitem_id_x(); asm volatile("" : "+v"(t)); return t; }
; __device__ __forceinline__ unsigned xb_add(unsigned* p, unsigned v) { return __hip_atomic_fetch_add(p, v, __ATOMIC_RELAXED, __HIP_MEMORY_SCOPE_AGENT); }
; __device__ __forceinline__ unsigned xb_xcc_id() { return (unsigned)__builtin_amdgcn_s_getreg((3 << 11) | 20) & 0xFu; }
; __device__ __forceinline__ void xcd_barrier(unsigned* bar, volatile LAS unsigned* st) {
;     asm volatile("s_waitcnt vmcnt(0)" ::: "memory");
;     __syncthreads();
;     if (get_tid() == 0) {
;         const unsigned x = xb_xcc_id();
;         __builtin_amdgcn_s_waitcnt(0);
;         unsigned nloc = st[0], nx = st[1];
;         if (nloc == 0u) { xcd_barrier_complete(bar, x, nloc, nx); st[0] = nloc; st[1] = nx; }
;         const unsigned old = xb_add(&bar[XB_XSUB(x)], 1u);
.LBB0_386:
	s_mov_b64 s[2:3], s[0:1]
	s_load_dword s4, s[2:3], 0xd8
	s_mov_b32 s11, 0
	s_waitcnt lgkmcnt(0)
	s_cmp_gt_i32 s4, 0
	s_cbranch_scc1 .LBB0_399
	s_load_dword s2, s[2:3], 0xdc
	s_waitcnt lgkmcnt(0)
	s_cmp_lt_i32 s2, 2
	s_cbranch_scc1 .LBB0_399
	v_mov_b32_e32 v161, 0
	v_mov_b32_e32 v254, 1
	s_add_i32 s2, 0, 0x25c00
	v_writelane_b32 v255, s2, 0
	s_add_i32 s2, 0, 0x25c04
	v_writelane_b32 v255, s2, 1
	s_mov_b64 s[4:5], s[0:1]
	s_add_u32 s28, s0, 0xe0
	s_addc_u32 s29, s1, 0
	s_waitcnt vmcnt(0)
	s_waitcnt vmcnt(0)
	v_mov_b32_e32 v0, v206
	s_barrier
	s_nop 0
	v_cmp_eq_u32_e32 vcc, 0, v0
	s_and_saveexec_b64 s[2:3], vcc
	s_cbranch_execz .Lmyb0_662
	v_readlane_b32 s7, v255, 0
	s_load_dwordx2 s[4:5], s[4:5], 0xd0
	s_getreg_b32 s6, hwreg(HW_REG_XCC_ID, 0, 4)
	v_mov_b32_e32 v0, s7
	s_waitcnt vmcnt(0) expcnt(0) lgkmcnt(0)
	ds_read_b32 v2, v0
	v_readlane_b32 s7, v255, 1
	s_and_b32 s10, s6, 15
	s_waitcnt lgkmcnt(0)
	v_cmp_ne_u32_e32 vcc, 0, v2
	v_mov_b32_e32 v0, s7
	ds_read_b32 v0, v0
	s_cbranch_vccnz .Lmyb0_626
	s_add_u32 s6, s4, 0x4200
	s_addc_u32 s7, s5, 0
	s_add_u32 s12, s4, 0x4400
	s_addc_u32 s13, s5, 0
	s_add_u32 s14, s4, 0x4500
	s_addc_u32 s15, s5, 0
	s_add_u32 s16, s4, 0x4600
	s_addc_u32 s17, s5, 0
	s_add_u32 s18, s4, 0x4700
	s_addc_u32 s19, s5, 0
	s_add_u32 s20, s4, 0x4800
	s_addc_u32 s21, s5, 0
	s_add_u32 s22, s4, 0x4900
	s_addc_u32 s23, s5, 0
	s_add_u32 s24, s4, 0x4a00
	s_addc_u32 s25, s5, 0
	s_add_u32 s26, s4, 0x4b00
	s_addc_u32 s27, s5, 0
	s_add_u32 s68, s4, 0x4c00
	s_addc_u32 s69, s5, 0
	s_add_u32 s70, s4, 0x4d00
	s_addc_u32 s71, s5, 0
	s_add_u32 s72, s4, 0x4e00
	s_addc_u32 s73, s5, 0
	s_add_u32 s74, s4, 0x4f00
	s_addc_u32 s75, s5, 0
	s_add_u32 s76, s4, 0x5000
	s_addc_u32 s77, s5, 0
	s_add_u32 s78, s4, 0x5100
	s_addc_u32 s79, s5, 0
	s_add_u32 s80, s4, 0x5200
	s_addc_u32 s81, s5, 0
	s_add_u32 s82, s4, 0x5300
	s_addc_u32 s83, s5, 0
	s_mov_b32 s31, 1
	s_branch .Lmyb0_614

; __device__ __forceinline__ unsigned xb_ld(unsigned* p)              { return __hip_atomic_load(p, __ATOMIC_RELAXED, __HIP_MEMORY_SCOPE_AGENT); }
; __device__ __forceinline__ void xcd_barrier_complete(unsigned* bar, unsigned x, unsigned& nloc, unsigned& nx) {
;     ...
;     for (;;) {
;         sum = 0u; cnt = 0u; mine = 0u;
; #pragma unroll
;         for (unsigned j = 0; j < 16; ++j) { const unsigned c = xb_ld(&bar[XB_XCNT(j)]); sum += c; cnt += (c > 0u) ? 1u : 0u; mine = (j == x) ? c : mine; }
.Lmyb0_614:

; __device__ __forceinline__ unsigned xb_ld(unsigned* p)              { return __hip_atomic_load(p, __ATOMIC_RELAXED, __HIP_MEMORY_SCOPE_AGENT); }
; __device__ __forceinline__ void xcd_barrier_complete(unsigned* bar, unsigned x, unsigned& nloc, unsigned& nx) {
;     ...
;     for (;;) {
;         sum = 0u; cnt = 0u; mine = 0u;
; #pragma unroll
;         for (unsigned j = 0; j < 16; ++j) { const unsigned c = xb_ld(&bar[XB_XCNT(j)]); sum += c; cnt += (c > 0u) ? 1u : 0u; mine = (j == x) ? c : mine; }
;         if (sum == G) break;
;         __builtin_amdgcn_s_sleep(1);
;         if ((++sp & 255u) == 0u) { if (xb_ld(&bar[XB_TMO])) break; if (sp > XB_SPIN_CAP) { atomicAdd(&bar[XB_TMO], 1u); break; } }
;     }
	global_load_dword v15, v161, s[12:13] sc1
	s_waitcnt lgkmcnt(0)
	global_load_dword v0, v161, s[14:15] sc1
	global_load_dword v1, v161, s[16:17] sc1
	global_load_dword v2, v161, s[18:19] sc1
	global_load_dword v3, v161, s[20:21] sc1
	global_load_dword v4, v161, s[22:23] sc1
	global_load_dword v5, v161, s[24:25] sc1
	global_load_dword v6, v161, s[26:27] sc1
	global_load_dword v7, v161, s[68:69] sc1
	global_load_dword v8, v161, s[70:71] sc1
	global_load_dword v9, v161, s[72:73] sc1
	global_load_dword v10, v161, s[74:75] sc1
	global_load_dword v11, v161, s[76:77] sc1
	global_load_dword v12, v161, s[78:79] sc1
	global_load_dword v13, v161, s[80:81] sc1
	global_load_dword v14, v161, s[82:83] sc1
	s_load_dword s35, s[28:29], 0x0
	s_mov_b64 s[84:85], -1
	s_mov_b64 s[86:87], -1
	s_waitcnt vmcnt(14)
	v_add_u32_e32 v16, v0, v15
	s_waitcnt vmcnt(13)
	v_add_u32_e32 v16, v16, v1
	s_waitcnt vmcnt(12)
	v_add_u32_e32 v16, v16, v2
	s_waitcnt vmcnt(11)
	v_add_u32_e32 v16, v16, v3
	s_waitcnt vmcnt(10)
	v_add_u32_e32 v16, v16, v4
	s_waitcnt vmcnt(9)
	v_add_u32_e32 v16, v16, v5
	s_waitcnt vmcnt(8)
	v_add_u32_e32 v16, v16, v6
	s_waitcnt vmcnt(7)
	v_add_u32_e32 v16, v16, v7
	s_waitcnt vmcnt(6)
	v_add_u32_e32 v16, v16, v8
	s_waitcnt vmcnt(5)
	v_add_u32_e32 v16, v16, v9
	s_waitcnt vmcnt(4)
	v_add_u32_e32 v16, v16, v10
	s_waitcnt vmcnt(3)
	v_add_u32_e32 v16, v16, v11
	s_waitcnt vmcnt(2)
	v_add_u32_e32 v16, v16, v12
	s_waitcnt vmcnt(1)
	v_add_u32_e32 v16, v16, v13
	s_waitcnt vmcnt(0)
	v_add_u32_e32 v16, v16, v14
	s_waitcnt lgkmcnt(0)
	v_cmp_eq_u32_e32 vcc, s35, v16
	s_cbranch_vccnz .Lmyb0_613
	s_and_b32 s35, s31, 0xff
	s_cmp_eq_u32 s35, 0
	s_mov_b64 s[88:89], -1
	s_sleep 1
	s_cbranch_scc1 .Lmyb0_618
	s_and_b64 vcc, exec, s[88:89]
	s_cbranch_vccz .Lmyb0_613

; __device__ __forceinline__ unsigned xb_ld(unsigned* p)              { return __hip_atomic_load(p, __ATOMIC_RELAXED, __HIP_MEMORY_SCOPE_AGENT); }
; #define XB_SPIN(cond, bar) do { unsigned _sp = 0; while (cond) { __builtin_amdgcn_s_sleep(1); \
;     if ((++_sp & 255u) == 0u) { if (xb_ld(&(bar)[XB_TMO])) break; if (_sp > XB_SPIN_CAP) { atomicAdd(&(bar)[XB_TMO], 1u); break; } } } } while (0)
; __device__ __forceinline__ void xcd_barrier(unsigned* bar, volatile LAS unsigned* st) {
;     ...
;             else XB_SPIN(xb_ld(&bar[XB_TOPGEN]) == tg, bar);
.Lmyb0_632:

	s_and_b32 s26, s10, 0xff
	s_mov_b64 s[24:25], -1
	s_cmp_lg_u32 s26, 0
	s_mov_b64 s[68:69], -1
	s_sleep 1
	s_cbranch_scc0 .Lmyb0_635
	s_and_b64 vcc, exec, s[68:69]
	s_cbranch_vccz .Lmyb0_631

; __device__ __forceinline__ unsigned xb_ld(unsigned* p)              { return __hip_atomic_load(p, __ATOMIC_RELAXED, __HIP_MEMORY_SCOPE_AGENT); }
; #define XB_SPIN(cond, bar) do { unsigned _sp = 0; while (cond) { __builtin_amdgcn_s_sleep(1); \
;     if ((++_sp & 255u) == 0u) { if (xb_ld(&(bar)[XB_TMO])) break; if (_sp > XB_SPIN_CAP) { atomicAdd(&(bar)[XB_TMO], 1u); break; } } } } while (0)
; __device__ __forceinline__ void xcd_barrier(unsigned* bar, volatile LAS unsigned* st) {
;     ...
;             XB_SPIN(xb_ld(&bar[XB_XGEN(x)]) == gen, bar);
.Lmyb0_649:

	s_and_b32 s24, s10, 0xff
	s_mov_b64 s[22:23], -1
	s_cmp_lg_u32 s24, 0
	s_mov_b64 s[26:27], -1
	s_sleep 1
	s_cbranch_scc0 .Lmyb0_652
	s_and_b64 vcc, exec, s[26:27]
	s_cbranch_vccz .Lmyb0_648

; #define IN(k) (PHON(k) && get_args()->ph_lo <= (k) && (k) < get_args()->ph_hi)
; __device__ __forceinline__ void xcd_barrier(unsigned* bar, volatile LAS unsigned* st) {
;     ...
;     __syncthreads();
; }
; __global__ void __launch_bounds__(512, 2) mega(Args a_unused) {
;     ...
;     for (int l = 0; l < 2; ++l) {
;         const int pb = 1 + 10 * l;
;         if (IN(pb)) ph_norm(l, 0, lds);
.Lmyb0_662:
	s_or_b64 exec, exec, s[2:3]
	s_waitcnt lgkmcnt(0)
	s_barrier
.LBB0_399:
	s_add_u32 s28, s0, 0xe0
	s_addc_u32 s29, s1, 0
	s_add_i32 s2, 0, 0x25c00
	s_mov_b32 s3, 0
	v_writelane_b32 v255, s2, 0
	s_add_i32 s2, 0, 0x25c04
	v_writelane_b32 v255, s2, 1
	s_add_i32 s2, 0, 0x13800
	v_writelane_b32 v255, s2, 2
	s_add_i32 s2, 0, 0x11400
	v_writelane_b32 v255, s2, 3
	v_mbcnt_lo_u32_b32 v0, -1, 0
	v_writelane_b32 v255, s2, 4
	s_movk_i32 s9, 0x5800
	v_mov_b32_e32 v161, 0
	s_movk_i32 s96, 0xc0
	s_movk_i32 s90, 0x1000
	s_mov_b32 s91, 0x38e38e39
	s_movk_i32 s93, 0xff
	s_movk_i32 s94, 0xff00
	v_mov_b32_e32 v207, 0x358637bd
	s_mov_b32 s34, 0x800000
	v_mov_b32_e32 v254, 1
	s_movk_i32 s50, 0x2000
	s_movk_i32 s86, 0x180
	s_movk_i32 s92, 0x2c00
	s_movk_i32 s41, 0x1800
	s_add_i32 s49, 0, 0x25800
	s_movk_i32 s37, 0x50
	s_mov_b32 s63, 0xbfb8aa3b
	s_mov_b32 s33, 0x3f317217
	s_mov_b32 s53, 0x7f800000
	s_movk_i32 s60, 0x140
	s_movk_i32 s61, 0x340
	s_movk_i32 s64, 0x380
	s_movk_i32 s65, 0x210
	s_mov_b32 s62, 0x41380000
	s_mov_b32 s97, 0x1fec0000
	v_mbcnt_hi_u32_b32 v212, -1, v0
	v_mov_b32_e32 v213, 0x41b17218
	v_mov_b32_e32 v214, 0x180
	v_mov_b64_e32 v[162:163], 0x100
	s_mov_b32 s95, 0x1ff20000
	s_mov_b32 s77, 0
	s_mov_b64 s[66:67], -1
	s_mov_b64 s[4:5], 0
	s_mov_b64 s[38:39], 0x80
	s_mov_b64 s[82:83], 0x25800000
	s_mov_b64 s[44:45], 0xc0000
	s_mov_b64 s[46:47], 0x3800
	v_writelane_b32 v255, s3, 5
	s_branch .LBB0_403
